# v112 + grid barrier: every 8th arrival of an XCD issues an early L2 write-back while it waits, so the last arrival's release write-back finds little left
# baseline (speedup 1.0000x reference)
; __device__ __forceinline__ unsigned xb_ld(unsigned* p)              { return __hip_atomic_load(p, __ATOMIC_RELAXED, __HIP_MEMORY_SCOPE_AGENT); }
; __device__ __forceinline__ unsigned xb_add(unsigned* p, unsigned v) { return __hip_atomic_fetch_add(p, v, __ATOMIC_RELAXED, __HIP_MEMORY_SCOPE_AGENT); }
; #define XB_SPIN(cond, bar) do { unsigned _sp = 0; while (cond) { __builtin_amdgcn_s_sleep(1); \
;     if ((++_sp & 255u) == 0u) { if (xb_ld(&(bar)[XB_TMO])) break; if (_sp > XB_SPIN_CAP) { atomicAdd(&(bar)[XB_TMO], 1u); break; } } } } while (0)
; __device__ __forceinline__ void xcd_barrier(const XcdBarrier& b) {
;     ...
;         const unsigned old = xb_add(&bar[XB_XSUB(b.x)], 1u);
;         const unsigned gen = old / nloc;
;         if (old + 1u == (gen + 1u) * nloc) {
;             __builtin_amdgcn_fence(__ATOMIC_RELEASE, "agent");
;             asm volatile("s_waitcnt vmcnt(0)" ::: "memory");
;             const unsigned og = xb_add(&bar[XB_TOP], 1u);
;             const unsigned tg = og / nx;
;             if (og + 1u == (tg + 1u) * nx) xb_add(&bar[XB_TOPGEN], 1u);
;             else XB_SPIN(xb_ld(&bar[XB_TOPGEN]) == tg, bar);
;             __builtin_amdgcn_fence(__ATOMIC_ACQUIRE, "agent");
;             xb_add(&bar[XB_XGEN(b.x)], 1u);
;             asm volatile("s_waitcnt vmcnt(0)" ::: "memory");
;         } else {
;             XB_SPIN(xb_ld(&bar[XB_XGEN(b.x)]) == gen, bar);
.LBB0_1219:
	s_or_b64 exec, exec, s[20:21]
	v_cvt_f32_u32_e32 v5, v3
	s_waitcnt vmcnt(0)
	v_readfirstlane_b32 s20, v4
	v_sub_u32_e32 v4, 0, v3
	v_rcp_iflag_f32_e32 v5, v5
	v_add_u32_e32 v6, s20, v0
	v_mul_f32_e32 v5, 0x4f7ffffe, v5
	v_cvt_u32_f32_e32 v5, v5
	v_mul_lo_u32 v0, v4, v5
	v_mul_hi_u32 v0, v5, v0
	v_add_u32_e32 v0, v5, v0
	v_mul_hi_u32 v0, v6, v0
	v_mul_lo_u32 v4, v0, v3
	v_sub_u32_e32 v4, v6, v4
	v_add_u32_e32 v5, 1, v0
	v_cmp_ge_u32_e32 vcc, v4, v3
	s_nop 1
	v_cndmask_b32_e32 v0, v0, v5, vcc
	v_sub_u32_e32 v5, v4, v3
	v_cndmask_b32_e32 v4, v4, v5, vcc
	v_add_u32_e32 v5, 1, v0
	v_cmp_ge_u32_e32 vcc, v4, v3
	v_add_u32_e32 v4, 1, v6
	s_nop 0
	v_cndmask_b32_e32 v0, v0, v5, vcc
	v_mul_lo_u32 v5, v3, v0
	v_add_u32_e32 v3, v5, v3
	v_cmp_ne_u32_e32 vcc, v4, v3
	s_and_saveexec_b64 s[20:21], vcc
	s_xor_b64 s[20:21], exec, s[20:21]
	s_cbranch_execz .LBB0_1233
	v_and_b32_e32 v2, 7, v6
	v_cmp_eq_u32_e32 vcc, 7, v2
	s_cbranch_vccz .Lbar_noflush
	buffer_wbl2 sc1
.Lbar_noflush:
	v_readlane_b32 s22, v252, 27
	v_readlane_b32 s23, v252, 28
	s_waitcnt lgkmcnt(0)
	s_nop 3
	global_load_dword v2, v1, s[22:23] sc1
	s_waitcnt vmcnt(0)
	v_cmp_eq_u32_e32 vcc, v2, v0
	s_and_saveexec_b64 s[22:23], vcc
	s_cbranch_execz .LBB0_1232
	s_mov_b32 s30, 1
	s_mov_b64 s[24:25], 0
	s_branch .LBB0_1223
